# waves 4-7 keep s_setprio 1 through the fused residual epilogue of the out-/down-projection (cleared at the thin GEMM entry)
# baseline (speedup 1.0000x reference)
; #define PG8_STAGE(bufoff, gbase, voff) do { _Pragma("unroll") for (int _i = 0; _i < 2; ++_i) \
;         __builtin_amdgcn_global_load_lds((const unsigned*)((const char*)(gbase) + (voff)[_i]), (LAS unsigned*)(lds + (bufoff) + ldsw + _i * 8192), 16, 0, 0); } while (0)
; #define PG8_LDA(dst, b, h) do { _Pragma("unroll") for (int m = 0; m < 4; ++m) _Pragma("unroll") for (int k = 0; k < 2; ++k) dst[m][k] = *(const LAS bf16x8*)(lds + PG8_SA(b, h) + aoff + m * 2048 + k * 1024); } while (0)
; #define PG8_LDB(dst, b, h) do { _Pragma("unroll") for (int n = 0; n < 2; ++n) _Pragma("unroll") for (int k = 0; k < 2; ++k) dst[n][k] = *(const LAS bf16x8*)(lds + PG8_SB(b, h) + boff + n * 2048 + k * 1024); } while (0)
; #define PG8_MMA(ai, bj, At, Bt) do { __builtin_amdgcn_s_setprio(1); _Pragma("unroll") for (int m = 0; m < 4; ++m) _Pragma("unroll") for (int n = 0; n < 2; ++n) _Pragma("unroll") for (int k = 0; k < 2; ++k) \
;         acc[ai][bj][m][n] = __builtin_amdgcn_mfma_f32_16x16x32_bf16(Bt[n][k], At[m][k], acc[ai][bj][m][n], 0, 0, 0); __builtin_amdgcn_s_setprio(0); } while (0)
; #define PG8_WAIT_V(n) asm volatile("s_waitcnt vmcnt(" #n ")" ::: "memory")
; #define PG8_WAIT_L(n) asm volatile("s_waitcnt lgkmcnt(" #n ")" ::: "memory")
; #define PG8_BAR __builtin_amdgcn_s_barrier()
; #define PG8_SCHED __builtin_amdgcn_sched_barrier(0)
; template <class Epi>
; __device__ __forceinline__ void gemm_phase(LAS unsigned char* lds, const Gemm g, const StaticOrder& S, const Epi& E) {
;     ...
;             PG8_LDB(B0, 0, 0); PG8_SCHED; PG8_LDA(At, 0, 0); PG8_STAGE(PG8_SA(1, 1), a1 + hstep, voffA);
;             PG8_WAIT_L(8); PG8_BAR; PG8_WAIT_L(0); PG8_MMA(0, 0, At, B0); PG8_BAR; PG8_SCHED;
;             PG8_LDB(B1, 0, 1); PG8_STAGE(PG8_SB(0, 0), b2, voffB);
;             PG8_BAR; PG8_WAIT_L(0); PG8_MMA(0, 1, At, B1); PG8_BAR;
;             PG8_LDA(At, 0, 1); PG8_STAGE(PG8_SA(0, 0), a2, voffA);
;             PG8_BAR; PG8_WAIT_L(0); PG8_MMA(1, 0, At, B0); PG8_BAR; PG8_SCHED;
;             PG8_STAGE(PG8_SB(0, 1), b2 + hstep, voffB);
;             PG8_WAIT_V(6); PG8_BAR; PG8_MMA(1, 1, At, B1); PG8_BAR;
;             PG8_LDB(B0, 1, 0); PG8_SCHED; PG8_LDA(At, 1, 0); PG8_STAGE(PG8_SA(0, 1), a2 + hstep, voffA);
;             PG8_WAIT_L(8); PG8_BAR; PG8_WAIT_L(0); PG8_MMA(0, 0, At, B0); PG8_BAR; PG8_SCHED;
.Lprio_164:
.LBB0_164:
	s_add_u32 s48, s46, s60
	s_addc_u32 s49, s47, s61
	s_add_u32 s48, s48, 0x100
	s_addc_u32 s49, s49, 0
	s_add_u32 s56, s70, s60
	s_addc_u32 s57, s71, s61
	s_add_i32 s58, 0, 0x10000
	v_add_u32_e32 v140, s58, v143
	ds_read_b128 v[148:151], v140
	ds_read_b128 v[152:155], v140 offset:1024
	ds_read_b128 v[156:159], v140 offset:2048
	ds_read_b128 v[172:175], v140 offset:3072
	s_cmpk_eq_i32 s60, 0x1500
	s_cselect_b32 s51, s37, s49
	s_cselect_b32 s50, s36, s48
	s_cselect_b32 s49, s45, s57
	s_cselect_b32 s48, s44, s56
	v_lshl_add_u64 v[140:141], v[136:137], 0, s[60:61]
	s_add_i32 m0, s53, 0xc000
	ds_read_b128 v[178:181], v147
	ds_read_b128 v[182:185], v147 offset:1024
	ds_read_b128 v[186:189], v147 offset:2048
	ds_read_b128 v[190:193], v147 offset:3072
	ds_read_b128 v[194:197], v147 offset:4096
	ds_read_b128 v[198:201], v147 offset:5120
	ds_read_b128 v[202:205], v147 offset:6144
	ds_read_b128 v[206:209], v147 offset:7168
	global_load_lds_dwordx4 v[140:141], off
	v_lshl_add_u64 v[140:141], v[138:139], 0, s[60:61]
	s_add_i32 m0, s53, 0xe000
	s_nop 0
	global_load_lds_dwordx4 v[140:141], off
	s_waitcnt lgkmcnt(8)
	s_barrier
	s_waitcnt lgkmcnt(0)
	s_waitcnt lgkmcnt(0)
	v_mfma_f32_16x16x32_bf16 v[126:129], v[148:151], v[178:181], v[126:129]
	v_mfma_f32_16x16x32_bf16 v[122:125], v[156:159], v[178:181], v[122:125]
	v_mfma_f32_16x16x32_bf16 v[110:113], v[148:151], v[186:189], v[110:113]
	v_mfma_f32_16x16x32_bf16 v[106:109], v[156:159], v[186:189], v[106:109]
	v_mfma_f32_16x16x32_bf16 v[94:97], v[148:151], v[194:197], v[94:97]
	v_mfma_f32_16x16x32_bf16 v[90:93], v[156:159], v[194:197], v[90:93]
	v_mfma_f32_16x16x32_bf16 v[78:81], v[148:151], v[202:205], v[78:81]
	v_mfma_f32_16x16x32_bf16 v[74:77], v[156:159], v[202:205], v[74:77]
	v_mfma_f32_16x16x32_bf16 v[126:129], v[152:155], v[182:185], v[126:129]
	v_mfma_f32_16x16x32_bf16 v[122:125], v[172:175], v[182:185], v[122:125]
	v_mfma_f32_16x16x32_bf16 v[110:113], v[152:155], v[190:193], v[110:113]
	v_mfma_f32_16x16x32_bf16 v[106:109], v[172:175], v[190:193], v[106:109]
	v_mfma_f32_16x16x32_bf16 v[94:97], v[152:155], v[198:201], v[94:97]
	v_mfma_f32_16x16x32_bf16 v[90:93], v[172:175], v[198:201], v[90:93]
	v_mfma_f32_16x16x32_bf16 v[78:81], v[152:155], v[206:209], v[78:81]
	v_mfma_f32_16x16x32_bf16 v[74:77], v[172:175], v[206:209], v[74:77]
	s_barrier
	s_add_i32 s56, 0, 0x14000
	v_add_u32_e32 v140, s56, v143
	s_add_i32 s57, s58, s52
	ds_read_b128 v[210:213], v140
	ds_read_b128 v[214:217], v140 offset:1024
	ds_read_b128 v[218:221], v140 offset:2048
	ds_read_b128 v[246:249], v140 offset:3072
	v_lshl_add_u64 v[140:141], s[48:49], 0, v[0:1]
	s_mov_b32 m0, s57
	v_lshl_add_u64 v[160:161], s[48:49], 0, v[130:131]
	global_load_lds_dwordx4 v[140:141], off
	s_add_i32 m0, s57, 0x2000
	s_nop 0
	global_load_lds_dwordx4 v[160:161], off
	s_barrier
	s_waitcnt lgkmcnt(0)
	s_waitcnt lgkmcnt(0)
	v_mfma_f32_16x16x32_bf16 v[118:121], v[210:213], v[178:181], v[118:121]
	v_mfma_f32_16x16x32_bf16 v[114:117], v[218:221], v[178:181], v[114:117]
	v_mfma_f32_16x16x32_bf16 v[102:105], v[210:213], v[186:189], v[102:105]
	v_mfma_f32_16x16x32_bf16 v[98:101], v[218:221], v[186:189], v[98:101]
	v_mfma_f32_16x16x32_bf16 v[86:89], v[210:213], v[194:197], v[86:89]
	v_mfma_f32_16x16x32_bf16 v[82:85], v[218:221], v[194:197], v[82:85]
	v_mfma_f32_16x16x32_bf16 v[70:73], v[210:213], v[202:205], v[70:73]
	v_mfma_f32_16x16x32_bf16 v[66:69], v[218:221], v[202:205], v[66:69]
	v_mfma_f32_16x16x32_bf16 v[118:121], v[214:217], v[182:185], v[118:121]
	v_mfma_f32_16x16x32_bf16 v[114:117], v[246:249], v[182:185], v[114:117]
	v_mfma_f32_16x16x32_bf16 v[102:105], v[214:217], v[190:193], v[102:105]
	v_mfma_f32_16x16x32_bf16 v[98:101], v[246:249], v[190:193], v[98:101]
	v_mfma_f32_16x16x32_bf16 v[86:89], v[214:217], v[198:201], v[86:89]
	v_mfma_f32_16x16x32_bf16 v[82:85], v[246:249], v[198:201], v[82:85]
	v_mfma_f32_16x16x32_bf16 v[70:73], v[214:217], v[206:209], v[70:73]
	v_mfma_f32_16x16x32_bf16 v[66:69], v[246:249], v[206:209], v[66:69]
	s_mov_b32 m0, s53
	v_lshl_add_u64 v[222:223], s[50:51], 0, v[0:1]
	s_barrier
	ds_read_b128 v[178:181], v147 offset:16384
	ds_read_b128 v[182:185], v147 offset:17408
	ds_read_b128 v[186:189], v147 offset:18432
	ds_read_b128 v[190:193], v147 offset:19456
	ds_read_b128 v[194:197], v147 offset:20480
	ds_read_b128 v[198:201], v147 offset:21504
	ds_read_b128 v[202:205], v147 offset:22528
	ds_read_b128 v[206:209], v147 offset:23552
	global_load_lds_dwordx4 v[222:223], off
	v_lshl_add_u64 v[236:237], s[50:51], 0, v[130:131]
	s_mov_b32 m0, s54
	s_nop 0
	global_load_lds_dwordx4 v[236:237], off
	s_barrier
	s_waitcnt lgkmcnt(0)
	s_waitcnt lgkmcnt(0)
	v_mfma_f32_16x16x32_bf16 v[62:65], v[148:151], v[178:181], v[62:65]
	v_mfma_f32_16x16x32_bf16 v[58:61], v[156:159], v[178:181], v[58:61]
	v_mfma_f32_16x16x32_bf16 v[46:49], v[148:151], v[186:189], v[46:49]
	v_mfma_f32_16x16x32_bf16 v[42:45], v[156:159], v[186:189], v[42:45]
	v_mfma_f32_16x16x32_bf16 v[30:33], v[148:151], v[194:197], v[30:33]
	v_mfma_f32_16x16x32_bf16 v[26:29], v[156:159], v[194:197], v[26:29]
	v_mfma_f32_16x16x32_bf16 v[14:17], v[148:151], v[202:205], v[14:17]
	v_mfma_f32_16x16x32_bf16 v[10:13], v[156:159], v[202:205], v[10:13]
	v_mfma_f32_16x16x32_bf16 v[62:65], v[152:155], v[182:185], v[62:65]
	v_mfma_f32_16x16x32_bf16 v[58:61], v[172:175], v[182:185], v[58:61]
	v_mfma_f32_16x16x32_bf16 v[46:49], v[152:155], v[190:193], v[46:49]
	v_mfma_f32_16x16x32_bf16 v[42:45], v[172:175], v[190:193], v[42:45]
	v_mfma_f32_16x16x32_bf16 v[30:33], v[152:155], v[198:201], v[30:33]
	v_mfma_f32_16x16x32_bf16 v[26:29], v[172:175], v[198:201], v[26:29]
	v_mfma_f32_16x16x32_bf16 v[14:17], v[152:155], v[206:209], v[14:17]
	v_mfma_f32_16x16x32_bf16 v[10:13], v[172:175], v[206:209], v[10:13]
	s_barrier
; #define PG8_STAGE(bufoff, gbase, voff) do { _Pragma("unroll") for (int _i = 0; _i < 2; ++_i) \
;         __builtin_amdgcn_global_load_lds((const unsigned*)((const char*)(gbase) + (voff)[_i]), (LAS unsigned*)(lds + (bufoff) + ldsw + _i * 8192), 16, 0, 0); } while (0)
; #define PG8_LDA(dst, b, h) do { _Pragma("unroll") for (int m = 0; m < 4; ++m) _Pragma("unroll") for (int k = 0; k < 2; ++k) dst[m][k] = *(const LAS bf16x8*)(lds + PG8_SA(b, h) + aoff + m * 2048 + k * 1024); } while (0)
; #define PG8_LDB(dst, b, h) do { _Pragma("unroll") for (int n = 0; n < 2; ++n) _Pragma("unroll") for (int k = 0; k < 2; ++k) dst[n][k] = *(const LAS bf16x8*)(lds + PG8_SB(b, h) + boff + n * 2048 + k * 1024); } while (0)
; #define PG8_MMA(ai, bj, At, Bt) do { __builtin_amdgcn_s_setprio(1); _Pragma("unroll") for (int m = 0; m < 4; ++m) _Pragma("unroll") for (int n = 0; n < 2; ++n) _Pragma("unroll") for (int k = 0; k < 2; ++k) \
;         acc[ai][bj][m][n] = __builtin_amdgcn_mfma_f32_16x16x32_bf16(Bt[n][k], At[m][k], acc[ai][bj][m][n], 0, 0, 0); __builtin_amdgcn_s_setprio(0); } while (0)
; #define PG8_WAIT_V(n) asm volatile("s_waitcnt vmcnt(" #n ")" ::: "memory")
; #define PG8_WAIT_L(n) asm volatile("s_waitcnt lgkmcnt(" #n ")" ::: "memory")
; #define PG8_BAR __builtin_amdgcn_s_barrier()
; #define PG8_SCHED __builtin_amdgcn_sched_barrier(0)
; template <class Epi>
; __device__ __forceinline__ void gemm_phase(LAS unsigned char* lds, const Gemm g, const StaticOrder& S, const Epi& E) {
;     ...
;             PG8_STAGE(PG8_SB(0, 1), b2 + hstep, voffB);
;             PG8_WAIT_V(6); PG8_BAR; PG8_MMA(1, 1, At, B1); PG8_BAR;
;             PG8_LDB(B0, 1, 0); PG8_SCHED; PG8_LDA(At, 1, 0); PG8_STAGE(PG8_SA(0, 1), a2 + hstep, voffA);
;             PG8_WAIT_L(8); PG8_BAR; PG8_WAIT_L(0); PG8_MMA(0, 0, At, B0); PG8_BAR; PG8_SCHED;
;             PG8_LDB(B1, 1, 1); PG8_STAGE(PG8_SB(1, 0), b3, voffB);
;             PG8_BAR; PG8_WAIT_L(0); PG8_MMA(0, 1, At, B1); PG8_BAR;
;             PG8_LDA(At, 1, 1); PG8_STAGE(PG8_SA(1, 0), a3, voffA);
;             PG8_BAR; PG8_WAIT_L(0); PG8_MMA(1, 0, At, B0); PG8_BAR; PG8_SCHED;
	s_add_u32 s58, s48, 0xb0000
	s_addc_u32 s59, s49, 0
	s_add_i32 s56, s56, s52
	v_lshl_add_u64 v[148:149], s[58:59], 0, v[0:1]
	s_mov_b32 m0, s56
	s_nop 0
	global_load_lds_dwordx4 v[148:149], off
	v_lshl_add_u64 v[148:149], s[58:59], 0, v[130:131]
	s_add_i32 m0, s56, 0x2000
	s_nop 0
	global_load_lds_dwordx4 v[148:149], off
	s_waitcnt vmcnt(6)
	s_barrier
	v_mfma_f32_16x16x32_bf16 v[54:57], v[210:213], v[178:181], v[54:57]
	v_mfma_f32_16x16x32_bf16 v[50:53], v[218:221], v[178:181], v[50:53]
	v_mfma_f32_16x16x32_bf16 v[38:41], v[210:213], v[186:189], v[38:41]
	v_mfma_f32_16x16x32_bf16 v[34:37], v[218:221], v[186:189], v[34:37]
	v_mfma_f32_16x16x32_bf16 v[22:25], v[210:213], v[194:197], v[22:25]
	v_mfma_f32_16x16x32_bf16 v[18:21], v[218:221], v[194:197], v[18:21]
	v_mfma_f32_16x16x32_bf16 v[6:9], v[210:213], v[202:205], v[6:9]
	v_mfma_f32_16x16x32_bf16 v[2:5], v[218:221], v[202:205], v[2:5]
	v_mfma_f32_16x16x32_bf16 v[54:57], v[214:217], v[182:185], v[54:57]
	v_mfma_f32_16x16x32_bf16 v[50:53], v[246:249], v[182:185], v[50:53]
	v_mfma_f32_16x16x32_bf16 v[38:41], v[214:217], v[190:193], v[38:41]
	v_mfma_f32_16x16x32_bf16 v[34:37], v[246:249], v[190:193], v[34:37]
	v_mfma_f32_16x16x32_bf16 v[22:25], v[214:217], v[198:201], v[22:25]
	v_mfma_f32_16x16x32_bf16 v[18:21], v[246:249], v[198:201], v[18:21]
	v_mfma_f32_16x16x32_bf16 v[6:9], v[214:217], v[206:209], v[6:9]
	v_mfma_f32_16x16x32_bf16 v[2:5], v[246:249], v[206:209], v[2:5]
	s_add_i32 s56, 0, 0x18000
	v_add_u32_e32 v172, s56, v143
	s_barrier
	ds_read_b128 v[148:151], v172
	ds_read_b128 v[152:155], v172 offset:1024
	ds_read_b128 v[156:159], v172 offset:2048
	ds_read_b128 v[172:175], v172 offset:3072
	s_add_u32 s50, s50, 0xb0000
	s_addc_u32 s51, s51, 0
	s_mov_b32 m0, s55
	v_lshl_add_u64 v[210:211], s[50:51], 0, v[0:1]
	ds_read_b128 v[178:181], v147 offset:32768
	ds_read_b128 v[182:185], v147 offset:33792
	ds_read_b128 v[186:189], v147 offset:34816
	ds_read_b128 v[190:193], v147 offset:35840
	ds_read_b128 v[194:197], v147 offset:36864
	ds_read_b128 v[198:201], v147 offset:37888
	ds_read_b128 v[202:205], v147 offset:38912
	ds_read_b128 v[206:209], v147 offset:39936
	global_load_lds_dwordx4 v[210:211], off
	v_lshl_add_u64 v[210:211], s[50:51], 0, v[130:131]
	s_mov_b32 m0, s63
	s_nop 0
	global_load_lds_dwordx4 v[210:211], off
	s_waitcnt lgkmcnt(8)
	s_barrier
	s_waitcnt lgkmcnt(0)
	s_waitcnt lgkmcnt(0)
	v_mfma_f32_16x16x32_bf16 v[126:129], v[148:151], v[178:181], v[126:129]
	v_mfma_f32_16x16x32_bf16 v[122:125], v[156:159], v[178:181], v[122:125]
	v_mfma_f32_16x16x32_bf16 v[110:113], v[148:151], v[186:189], v[110:113]
	v_mfma_f32_16x16x32_bf16 v[106:109], v[156:159], v[186:189], v[106:109]
	v_mfma_f32_16x16x32_bf16 v[94:97], v[148:151], v[194:197], v[94:97]
	v_mfma_f32_16x16x32_bf16 v[90:93], v[156:159], v[194:197], v[90:93]
	v_mfma_f32_16x16x32_bf16 v[78:81], v[148:151], v[202:205], v[78:81]
	v_mfma_f32_16x16x32_bf16 v[74:77], v[156:159], v[202:205], v[74:77]
	v_mfma_f32_16x16x32_bf16 v[126:129], v[152:155], v[182:185], v[126:129]
	v_mfma_f32_16x16x32_bf16 v[122:125], v[172:175], v[182:185], v[122:125]
	v_mfma_f32_16x16x32_bf16 v[110:113], v[152:155], v[190:193], v[110:113]
	v_mfma_f32_16x16x32_bf16 v[106:109], v[172:175], v[190:193], v[106:109]
	v_mfma_f32_16x16x32_bf16 v[94:97], v[152:155], v[198:201], v[94:97]
	v_mfma_f32_16x16x32_bf16 v[90:93], v[172:175], v[198:201], v[90:93]
	v_mfma_f32_16x16x32_bf16 v[78:81], v[152:155], v[206:209], v[78:81]
	v_mfma_f32_16x16x32_bf16 v[74:77], v[172:175], v[206:209], v[74:77]
	s_barrier
	s_add_i32 s50, 0, 0x1c000
	s_add_i32 s51, s56, s52
	v_add_u32_e32 v177, s50, v143
	v_lshl_add_u64 v[140:141], v[140:141], 0, s[28:29]
	s_mov_b32 m0, s51
	ds_read_b128 v[210:213], v177
	ds_read_b128 v[214:217], v177 offset:1024
	ds_read_b128 v[218:221], v177 offset:2048
	ds_read_b128 v[246:249], v177 offset:3072
	global_load_lds_dwordx4 v[140:141], off
	v_lshl_add_u64 v[140:141], v[160:161], 0, s[28:29]
	s_add_i32 m0, s51, 0x2000
	s_nop 0
	global_load_lds_dwordx4 v[140:141], off
	s_barrier
	s_waitcnt lgkmcnt(0)
	s_waitcnt lgkmcnt(0)
	v_mfma_f32_16x16x32_bf16 v[118:121], v[210:213], v[178:181], v[118:121]
	v_mfma_f32_16x16x32_bf16 v[114:117], v[218:221], v[178:181], v[114:117]
	v_mfma_f32_16x16x32_bf16 v[102:105], v[210:213], v[186:189], v[102:105]
	v_mfma_f32_16x16x32_bf16 v[98:101], v[218:221], v[186:189], v[98:101]
	v_mfma_f32_16x16x32_bf16 v[86:89], v[210:213], v[194:197], v[86:89]
	v_mfma_f32_16x16x32_bf16 v[82:85], v[218:221], v[194:197], v[82:85]
	v_mfma_f32_16x16x32_bf16 v[70:73], v[210:213], v[202:205], v[70:73]
	v_mfma_f32_16x16x32_bf16 v[66:69], v[218:221], v[202:205], v[66:69]
	v_mfma_f32_16x16x32_bf16 v[118:121], v[214:217], v[182:185], v[118:121]
	v_mfma_f32_16x16x32_bf16 v[114:117], v[246:249], v[182:185], v[114:117]
	v_mfma_f32_16x16x32_bf16 v[102:105], v[214:217], v[190:193], v[102:105]
	v_mfma_f32_16x16x32_bf16 v[98:101], v[246:249], v[190:193], v[98:101]
	v_mfma_f32_16x16x32_bf16 v[86:89], v[214:217], v[198:201], v[86:89]
	v_mfma_f32_16x16x32_bf16 v[82:85], v[246:249], v[198:201], v[82:85]
	v_mfma_f32_16x16x32_bf16 v[70:73], v[214:217], v[206:209], v[70:73]
	v_mfma_f32_16x16x32_bf16 v[66:69], v[246:249], v[206:209], v[66:69]
	s_mov_b32 m0, s64
	v_lshl_add_u64 v[140:141], v[222:223], 0, s[28:29]
	s_barrier
	ds_read_b128 v[178:181], v147 offset:49152
	ds_read_b128 v[182:185], v147 offset:50176
	ds_read_b128 v[186:189], v147 offset:51200
	ds_read_b128 v[190:193], v147 offset:52224
	ds_read_b128 v[194:197], v147 offset:53248
	ds_read_b128 v[198:201], v147 offset:54272
	ds_read_b128 v[202:205], v147 offset:55296
	ds_read_b128 v[206:209], v147 offset:56320
	global_load_lds_dwordx4 v[140:141], off
	v_lshl_add_u64 v[140:141], v[236:237], 0, s[28:29]
	s_mov_b32 m0, s65
	s_nop 0
	global_load_lds_dwordx4 v[140:141], off
	s_barrier
; __device__ __forceinline__ u64 ss_fix(float ss) { return (u64)(ss * 1048576.f + 0.5f); }
; __device__ __forceinline__ unsigned pk2(float lo, float hi) { unsigned r; asm volatile("v_cvt_pk_bf16_f32 %0, %1, %2" : "=v"(r) : "v"(lo), "v"(hi)); return r; }
; __device__ __forceinline__ float shfl_xor_(float v, int o, int lane) { return shfl_idx(v, lane ^ o); }
; #define PG8_STAGE(bufoff, gbase, voff) do { _Pragma("unroll") for (int _i = 0; _i < 2; ++_i) \
;         __builtin_amdgcn_global_load_lds((const unsigned*)((const char*)(gbase) + (voff)[_i]), (LAS unsigned*)(lds + (bufoff) + ldsw + _i * 8192), 16, 0, 0); } while (0)
; #define PG8_WAIT_V(n) asm volatile("s_waitcnt vmcnt(" #n ")" ::: "memory")
; #define PG8_WAIT_L(n) asm volatile("s_waitcnt lgkmcnt(" #n ")" ::: "memory")
; #define PG8_BAR __builtin_amdgcn_s_barrier()
; #define PG8_SCHED __builtin_amdgcn_sched_barrier(0)
; template <class Epi>
; __device__ __forceinline__ void gemm_phase(LAS unsigned char* lds, const Gemm g, const StaticOrder& S, const Epi& E) {
;     ...
;             PG8_BAR; PG8_WAIT_L(0); PG8_MMA(1, 0, At, B0); PG8_BAR; PG8_SCHED;
;             PG8_STAGE(PG8_SB(1, 1), b3 + hstep, voffB);
;             PG8_WAIT_V(6); PG8_BAR; PG8_MMA(1, 1, At, B1); PG8_BAR;
;     __device__ __forceinline__ void operator()(const f32x4 (&acc)[2][2][4][2], const Unit& u, int wr, int wc, int fr, int fq) const {
;         const int row0 = u.pm * BM + wr * 64 + fr, col0 = u.pn * BM + wc * 32 + 4 * fq, lane = fr | (fq << 4);
; #pragma unroll
;         for (int ai = 0; ai < 2; ++ai)
; #pragma unroll
;             for (int m = 0; m < 4; ++m) { const int row = row0 + ai * HALF + m * 16; bf16_t* xbp = xb + (size_t)row * ldc + col0;
;                 float ss = 0.f;
; #pragma unroll
;                 for (int bj = 0; bj < 2; ++bj)
; #pragma unroll
;                     for (int n = 0; n < 2; ++n) { u32x2* pp = (u32x2*)(xbp + bj * HALF + n * 16); float o[4]; unpack4(*pp, o);
;                         u32x2 w; w.x = pk2(o[0] + acc[ai][bj][m][n][0], o[1] + acc[ai][bj][m][n][1]); w.y = pk2(o[2] + acc[ai][bj][m][n][2], o[3] + acc[ai][bj][m][n][3]); *pp = w;
;                         unpack4(w, o); ss += o[0] * o[0] + o[1] * o[1] + o[2] * o[2] + o[3] * o[3]; }
;                 ss += shfl_xor_(ss, 16, lane); ss += shfl_xor_(ss, 32, lane);
;                 if (fq == 0) atomicAdd(rss + row, ss_fix(ss)); }
	s_waitcnt lgkmcnt(0)
	s_waitcnt lgkmcnt(0)
	v_mfma_f32_16x16x32_bf16 v[62:65], v[148:151], v[178:181], v[62:65]
	v_mfma_f32_16x16x32_bf16 v[58:61], v[156:159], v[178:181], v[58:61]
	v_mfma_f32_16x16x32_bf16 v[46:49], v[148:151], v[186:189], v[46:49]
	v_mfma_f32_16x16x32_bf16 v[42:45], v[156:159], v[186:189], v[42:45]
	v_mfma_f32_16x16x32_bf16 v[30:33], v[148:151], v[194:197], v[30:33]
	v_mfma_f32_16x16x32_bf16 v[26:29], v[156:159], v[194:197], v[26:29]
	v_mfma_f32_16x16x32_bf16 v[14:17], v[148:151], v[202:205], v[14:17]
	v_mfma_f32_16x16x32_bf16 v[10:13], v[156:159], v[202:205], v[10:13]
	v_mfma_f32_16x16x32_bf16 v[62:65], v[152:155], v[182:185], v[62:65]
	v_mfma_f32_16x16x32_bf16 v[58:61], v[172:175], v[182:185], v[58:61]
	v_mfma_f32_16x16x32_bf16 v[46:49], v[152:155], v[190:193], v[46:49]
	v_mfma_f32_16x16x32_bf16 v[42:45], v[172:175], v[190:193], v[42:45]
	v_mfma_f32_16x16x32_bf16 v[30:33], v[152:155], v[198:201], v[30:33]
	v_mfma_f32_16x16x32_bf16 v[26:29], v[172:175], v[198:201], v[26:29]
	v_mfma_f32_16x16x32_bf16 v[14:17], v[152:155], v[206:209], v[14:17]
	v_mfma_f32_16x16x32_bf16 v[10:13], v[172:175], v[206:209], v[10:13]
	s_barrier
	s_add_u32 s48, s48, 0xb0080
	s_addc_u32 s49, s49, 0
	s_add_i32 s50, s50, s52
	v_lshl_add_u64 v[140:141], s[48:49], 0, v[0:1]
	s_mov_b32 m0, s50
	s_nop 0
	global_load_lds_dwordx4 v[140:141], off
	v_lshl_add_u64 v[140:141], s[48:49], 0, v[130:131]
	s_add_i32 m0, s50, 0x2000
	s_nop 0
	global_load_lds_dwordx4 v[140:141], off
	s_waitcnt vmcnt(6)
	s_barrier
	v_mfma_f32_16x16x32_bf16 v[54:57], v[210:213], v[178:181], v[54:57]
	v_mfma_f32_16x16x32_bf16 v[50:53], v[218:221], v[178:181], v[50:53]
	v_mfma_f32_16x16x32_bf16 v[38:41], v[210:213], v[186:189], v[38:41]
	v_mfma_f32_16x16x32_bf16 v[34:37], v[218:221], v[186:189], v[34:37]
	v_mfma_f32_16x16x32_bf16 v[22:25], v[210:213], v[194:197], v[22:25]
	v_mfma_f32_16x16x32_bf16 v[18:21], v[218:221], v[194:197], v[18:21]
	v_mfma_f32_16x16x32_bf16 v[6:9], v[210:213], v[202:205], v[6:9]
	v_mfma_f32_16x16x32_bf16 v[2:5], v[218:221], v[202:205], v[2:5]
	v_mfma_f32_16x16x32_bf16 v[54:57], v[214:217], v[182:185], v[54:57]
	v_mfma_f32_16x16x32_bf16 v[50:53], v[246:249], v[182:185], v[50:53]
	v_mfma_f32_16x16x32_bf16 v[38:41], v[214:217], v[190:193], v[38:41]
	v_mfma_f32_16x16x32_bf16 v[34:37], v[246:249], v[190:193], v[34:37]
	v_mfma_f32_16x16x32_bf16 v[22:25], v[214:217], v[198:201], v[22:25]
	v_mfma_f32_16x16x32_bf16 v[18:21], v[246:249], v[198:201], v[18:21]
	v_mfma_f32_16x16x32_bf16 v[6:9], v[214:217], v[206:209], v[6:9]
	v_mfma_f32_16x16x32_bf16 v[2:5], v[246:249], v[206:209], v[2:5]
	s_add_i32 s93, s93, 2
	s_add_u32 s60, s60, 0x100
	s_addc_u32 s61, s61, 0
	s_cmp_gt_u32 s93, 41
	s_barrier
	s_cbranch_scc0 .LBB0_164
	s_add_u32 s48, s70, 0xffffff00
	s_addc_u32 s49, s71, -1
	s_and_b64 vcc, exec, s[0:1]
	s_movk_i32 s93, 0x1000
	s_cbranch_vccz .LBB0_183
	v_lshl_add_u32 v140, s68, 8, v142
	v_ashrrev_i32_e32 v141, 31, v140
	v_readlane_b32 s0, v252, 51
	v_lshl_or_b32 v138, s67, 8, v144
	v_lshlrev_b64 v[136:137], 11, v[140:141]
	v_readlane_b32 s1, v252, 52
	v_ashrrev_i32_e32 v139, 31, v138
	s_nop 0
	v_lshl_add_u64 v[136:137], s[0:1], 0, v[136:137]
	v_lshl_add_u64 v[136:137], v[138:139], 1, v[136:137]
	global_load_dwordx2 v[148:149], v[136:137], off
	s_waitcnt vmcnt(0)
	v_lshlrev_b32_e32 v150, 16, v148
	v_and_b32_e32 v148, 0xffff0000, v148
	v_lshlrev_b32_e32 v151, 16, v149
	v_and_b32_e32 v149, 0xffff0000, v149
	v_add_f32_e32 v126, v126, v150
	v_add_f32_e32 v127, v127, v148
	v_add_f32_e32 v128, v128, v151
	v_add_f32_e32 v129, v129, v149
	v_cvt_pk_bf16_f32 v126, v126, v127
	v_cvt_pk_bf16_f32 v127, v128, v129
	global_load_dwordx2 v[128:129], v[136:137], off offset:32
	s_waitcnt vmcnt(0)
	v_lshlrev_b32_e32 v148, 16, v128
	v_and_b32_e32 v128, 0xffff0000, v128
	v_lshlrev_b32_e32 v149, 16, v129
	v_and_b32_e32 v129, 0xffff0000, v129
	v_add_f32_e32 v122, v122, v148
	v_add_f32_e32 v123, v123, v128
	v_add_f32_e32 v124, v124, v149
	v_add_f32_e32 v125, v125, v129
	global_store_dwordx2 v[136:137], v[126:127], off
	v_cvt_pk_bf16_f32 v122, v122, v123
	v_cvt_pk_bf16_f32 v123, v124, v125
	global_load_dwordx2 v[124:125], v[136:137], off offset:256
	s_waitcnt vmcnt(0)
	v_lshlrev_b32_e32 v128, 16, v124
	v_and_b32_e32 v124, 0xffff0000, v124
	v_lshlrev_b32_e32 v129, 16, v125
	v_and_b32_e32 v125, 0xffff0000, v125
	v_add_f32_e32 v118, v118, v128
	v_add_f32_e32 v119, v119, v124
	v_add_f32_e32 v120, v120, v129
	v_add_f32_e32 v121, v121, v125
	global_store_dwordx2 v[136:137], v[122:123], off offset:32
	v_cvt_pk_bf16_f32 v118, v118, v119
	v_cvt_pk_bf16_f32 v119, v120, v121
	global_load_dwordx2 v[120:121], v[136:137], off offset:288
	v_and_b32_e32 v125, 0xffff0000, v126
	v_lshlrev_b32_e32 v124, 16, v126
	v_mul_f32_e32 v125, v125, v125
	v_fmac_f32_e32 v125, v124, v124
	v_lshlrev_b32_e32 v124, 16, v122
	v_and_b32_e32 v122, 0xffff0000, v122
	v_lshlrev_b32_e32 v126, 16, v127
	v_mul_f32_e32 v122, v122, v122
	v_fmac_f32_e32 v125, v126, v126
	v_lshlrev_b32_e32 v126, 16, v123
	v_fmac_f32_e32 v122, v124, v124
	v_and_b32_e32 v123, 0xffff0000, v123
	v_fmac_f32_e32 v122, v126, v126
	v_fmac_f32_e32 v122, v123, v123
	global_store_dwordx2 v[136:137], v[118:119], off offset:256
	v_lshlrev_b32_e32 v123, 16, v118
	v_and_b32_e32 v118, 0xffff0000, v118
	v_mul_f32_e32 v118, v118, v118
	v_and_b32_e32 v127, 0xffff0000, v127
	v_lshlrev_b32_e32 v124, 16, v119
	v_fmac_f32_e32 v118, v123, v123
	v_fmac_f32_e32 v125, v127, v127
	v_and_b32_e32 v119, 0xffff0000, v119
	v_fmac_f32_e32 v118, v124, v124
	v_add_f32_e32 v122, v125, v122
	v_fmac_f32_e32 v118, v119, v119
	v_add_f32_e32 v118, v122, v118
	s_waitcnt vmcnt(0)
	v_lshlrev_b32_e32 v119, 16, v120
	v_and_b32_e32 v120, 0xffff0000, v120
	v_lshlrev_b32_e32 v122, 16, v121
	v_and_b32_e32 v121, 0xffff0000, v121
	v_add_f32_e32 v114, v114, v119
	v_add_f32_e32 v115, v115, v120
	v_add_f32_e32 v117, v117, v121
	v_add_f32_e32 v116, v116, v122
	v_cvt_pk_bf16_f32 v114, v114, v115
	v_cvt_pk_bf16_f32 v115, v116, v117
	global_store_dwordx2 v[136:137], v[114:115], off offset:288
	v_and_b32_e32 v117, 0xffff0000, v114
	v_lshlrev_b32_e32 v116, 16, v114
	v_mul_f32_e32 v117, v117, v117
	v_lshlrev_b32_e32 v119, 16, v115
	v_fmac_f32_e32 v117, v116, v116
	v_and_b32_e32 v120, 0xffff0000, v115
	v_fmac_f32_e32 v117, v119, v119
	v_fmac_f32_e32 v117, v120, v120
	v_add_f32_e32 v116, v118, v117
	ds_bpermute_b32 v117, v145, v116
	v_lshl_add_u64 v[114:115], v[140:141], 3, s[72:73]
	s_waitcnt lgkmcnt(0)
	v_add_f32_e32 v116, v116, v117
	ds_bpermute_b32 v117, v146, v116
	s_and_saveexec_b64 s[0:1], s[40:41]
	v_readlane_b32 s84, v254, 44
	v_readlane_b32 s85, v254, 45
	s_cbranch_execz .LBB0_168
	s_waitcnt lgkmcnt(0)
	v_add_f32_e32 v116, v116, v117
	s_mov_b32 s46, 0x49800000
	v_fma_f32 v116, v116, s46, 0.5
	v_trunc_f32_e32 v116, v116
	v_mul_f32_e32 v117, 0x2f800000, v116
	v_floor_f32_e32 v117, v117
	v_fmac_f32_e32 v116, 0xcf800000, v117
	v_cvt_u32_f32_e32 v116, v116
	v_cvt_u32_f32_e32 v117, v117
	global_atomic_add_x2 v[114:115], v[116:117], off

; #define LAS __attribute__((address_space(3)))
; #define TIDX opaque_tid()
; template <int K, int MODE  >
; __device__ __forceinline__ void thin_gemm(LAS unsigned char* lds, const bf16_t* A, const bf16_t* Bt, int N, void* out, int ldc, bf16_t* xb, u64* rss) {
;     const int tid = TIDX, wid = tid >> 6, lane = tid & 63, fr = lane & 15, fq = lane >> 4;
;     constexpr int KW = K / 8, STEPS = KW / 32;
;     const int ntask = (N / 16) * 8;
;     LAS f32x4* red = (LAS f32x4*)lds;
;     const int per = (ntask + (int)gridDim.x - 1) / (int)gridDim.x, t0 = blockIdx.x * per, t1 = min(ntask, t0 + per);
;     for (int base = t0; base < t1; base += 8) {
;         const int nr = min(8, t1 - base);
; #pragma unroll (STEPS <= 4 ? 4 : 2)
;         for (int i = 0; i < nr; ++i) {
;             const int t = base + i, ct = t >> 3, rt = t & 7;
;             const bf16_t* ap = A + (size_t)(rt * 16 + fr) * K + wid * KW + 8 * fq;
;             const bf16_t* bp = Bt + (size_t)(ct * 16 + fr) * K + wid * KW + 8 * fq;
.LBB0_192:
	s_setprio 0
	v_readlane_b32 s0, v253, 6
	v_readlane_b32 s1, v253, 7
	v_mov_b32_e32 v10, v163
	s_andn2_b64 vcc, exec, s[0:1]
	v_readlane_b32 s30, v253, 8
	s_cbranch_vccnz .LBB0_201
	v_ashrrev_i32_e32 v6, 6, v10
	s_movk_i32 s0, 0x160
	v_mul_lo_u32 v2, v6, s0
	v_ashrrev_i32_e32 v3, 31, v2
	v_readlane_b32 s0, v250, 26
	v_lshlrev_b64 v[4:5], 1, v[2:3]
	v_readlane_b32 s1, v250, 27
	v_and_b32_e32 v13, 63, v10
	v_and_b32_e32 v0, 48, v10
	v_lshl_add_u64 v[2:3], s[0:1], 0, v[4:5]
	v_lshl_add_u64 v[4:5], s[78:79], 0, v[4:5]
	v_lshl_add_u32 v9, v13, 4, 0
	v_lshl_add_u64 v[2:3], v[2:3], 0, v[0:1]
	v_lshl_add_u64 v[4:5], v[4:5], 0, v[0:1]
	v_and_b32_e32 v0, 0xfffffc0, v10
	v_lshl_add_u32 v8, v0, 4, v9
	v_lshrrev_b32_e32 v0, 2, v10
	v_and_b32_e32 v7, 15, v10
	s_add_u32 s36, s72, 0x20000
	v_and_b32_e32 v10, 12, v0
	v_lshlrev_b32_e32 v0, 2, v13
	s_addc_u32 s37, s73, 0
	v_lshl_add_u32 v9, v6, 13, v9
	v_xor_b32_e32 v11, 64, v0
	v_xor_b32_e32 v12, 0x80, v0
	v_cmp_gt_u32_e32 vcc, 16, v13
	v_readlane_b32 s2, v253, 35
	v_readlane_b32 s3, v253, 33
	v_readlane_b32 s24, v253, 9
	v_readlane_b32 s26, v253, 34
	s_branch .LBB0_195

; #define PG8_STAGE(bufoff, gbase, voff) do { _Pragma("unroll") for (int _i = 0; _i < 2; ++_i) \
;         __builtin_amdgcn_global_load_lds((const unsigned*)((const char*)(gbase) + (voff)[_i]), (LAS unsigned*)(lds + (bufoff) + ldsw + _i * 8192), 16, 0, 0); } while (0)
; #define PG8_LDA(dst, b, h) do { _Pragma("unroll") for (int m = 0; m < 4; ++m) _Pragma("unroll") for (int k = 0; k < 2; ++k) dst[m][k] = *(const LAS bf16x8*)(lds + PG8_SA(b, h) + aoff + m * 2048 + k * 1024); } while (0)
; #define PG8_LDB(dst, b, h) do { _Pragma("unroll") for (int n = 0; n < 2; ++n) _Pragma("unroll") for (int k = 0; k < 2; ++k) dst[n][k] = *(const LAS bf16x8*)(lds + PG8_SB(b, h) + boff + n * 2048 + k * 1024); } while (0)
; #define PG8_MMA(ai, bj, At, Bt) do { __builtin_amdgcn_s_setprio(1); _Pragma("unroll") for (int m = 0; m < 4; ++m) _Pragma("unroll") for (int n = 0; n < 2; ++n) _Pragma("unroll") for (int k = 0; k < 2; ++k) \
;         acc[ai][bj][m][n] = __builtin_amdgcn_mfma_f32_16x16x32_bf16(Bt[n][k], At[m][k], acc[ai][bj][m][n], 0, 0, 0); __builtin_amdgcn_s_setprio(0); } while (0)
; #define PG8_WAIT_V(n) asm volatile("s_waitcnt vmcnt(" #n ")" ::: "memory")
; #define PG8_WAIT_L(n) asm volatile("s_waitcnt lgkmcnt(" #n ")" ::: "memory")
; #define PG8_BAR __builtin_amdgcn_s_barrier()
; #define PG8_SCHED __builtin_amdgcn_sched_barrier(0)
; template <class Epi>
; __device__ __forceinline__ void gemm_phase(LAS unsigned char* lds, const Gemm g, const StaticOrder& S, const Epi& E) {
;     ...
;             PG8_LDB(B0, 0, 0); PG8_SCHED; PG8_LDA(At, 0, 0); PG8_STAGE(PG8_SA(1, 1), a1 + hstep, voffA);
;             PG8_WAIT_L(8); PG8_BAR; PG8_WAIT_L(0); PG8_MMA(0, 0, At, B0); PG8_BAR; PG8_SCHED;
;             PG8_LDB(B1, 0, 1); PG8_STAGE(PG8_SB(0, 0), b2, voffB);
;             PG8_BAR; PG8_WAIT_L(0); PG8_MMA(0, 1, At, B1); PG8_BAR;
;             PG8_LDA(At, 0, 1); PG8_STAGE(PG8_SA(0, 0), a2, voffA);
;             PG8_BAR; PG8_WAIT_L(0); PG8_MMA(1, 0, At, B0); PG8_BAR; PG8_SCHED;
;             PG8_STAGE(PG8_SB(0, 1), b2 + hstep, voffB);
;             PG8_WAIT_V(6); PG8_BAR; PG8_MMA(1, 1, At, B1); PG8_BAR;
;             PG8_LDB(B0, 1, 0); PG8_SCHED; PG8_LDA(At, 1, 0); PG8_STAGE(PG8_SA(0, 1), a2 + hstep, voffA);
;             PG8_WAIT_L(8); PG8_BAR; PG8_WAIT_L(0); PG8_MMA(0, 0, At, B0); PG8_BAR; PG8_SCHED;
.Lprio_258:
.LBB0_258:
	s_add_u32 s46, s48, s50
	s_addc_u32 s47, s49, s51
	s_add_u32 s46, s46, 0x100
	s_addc_u32 s47, s47, 0
	s_add_u32 s52, s68, s50
	s_addc_u32 s53, s69, s51
	s_add_i32 s71, 0, 0x10000
	v_add_u32_e32 v140, s71, v143
	ds_read_b128 v[148:151], v140
	ds_read_b128 v[152:155], v140 offset:1024
	ds_read_b128 v[156:159], v140 offset:2048
	ds_read_b128 v[172:175], v140 offset:3072
	s_cmpk_eq_i32 s50, 0xb00
	s_cselect_b32 s47, s37, s47
	s_cselect_b32 s46, s36, s46
	s_cselect_b32 s53, s45, s53
	s_cselect_b32 s52, s44, s52
	v_lshl_add_u64 v[140:141], v[136:137], 0, s[50:51]
	s_add_i32 m0, s55, 0xc000
	ds_read_b128 v[178:181], v147
	ds_read_b128 v[182:185], v147 offset:1024
	ds_read_b128 v[186:189], v147 offset:2048
	ds_read_b128 v[190:193], v147 offset:3072
	ds_read_b128 v[194:197], v147 offset:4096
	ds_read_b128 v[198:201], v147 offset:5120
	ds_read_b128 v[202:205], v147 offset:6144
	ds_read_b128 v[206:209], v147 offset:7168
	global_load_lds_dwordx4 v[140:141], off
	v_lshl_add_u64 v[140:141], v[138:139], 0, s[50:51]
	s_add_i32 m0, s55, 0xe000
	s_nop 0
	global_load_lds_dwordx4 v[140:141], off
	s_waitcnt lgkmcnt(8)
	s_barrier
	s_waitcnt lgkmcnt(0)
	s_waitcnt lgkmcnt(0)
	v_mfma_f32_16x16x32_bf16 v[126:129], v[148:151], v[178:181], v[126:129]
	v_mfma_f32_16x16x32_bf16 v[122:125], v[156:159], v[178:181], v[122:125]
	v_mfma_f32_16x16x32_bf16 v[110:113], v[148:151], v[186:189], v[110:113]
	v_mfma_f32_16x16x32_bf16 v[106:109], v[156:159], v[186:189], v[106:109]
	v_mfma_f32_16x16x32_bf16 v[94:97], v[148:151], v[194:197], v[94:97]
	v_mfma_f32_16x16x32_bf16 v[90:93], v[156:159], v[194:197], v[90:93]
	v_mfma_f32_16x16x32_bf16 v[78:81], v[148:151], v[202:205], v[78:81]
	v_mfma_f32_16x16x32_bf16 v[74:77], v[156:159], v[202:205], v[74:77]
	v_mfma_f32_16x16x32_bf16 v[126:129], v[152:155], v[182:185], v[126:129]
	v_mfma_f32_16x16x32_bf16 v[122:125], v[172:175], v[182:185], v[122:125]
	v_mfma_f32_16x16x32_bf16 v[110:113], v[152:155], v[190:193], v[110:113]
	v_mfma_f32_16x16x32_bf16 v[106:109], v[172:175], v[190:193], v[106:109]
	v_mfma_f32_16x16x32_bf16 v[94:97], v[152:155], v[198:201], v[94:97]
	v_mfma_f32_16x16x32_bf16 v[90:93], v[172:175], v[198:201], v[90:93]
	v_mfma_f32_16x16x32_bf16 v[78:81], v[152:155], v[206:209], v[78:81]
	v_mfma_f32_16x16x32_bf16 v[74:77], v[172:175], v[206:209], v[74:77]
	s_barrier
	s_add_i32 s93, 0, 0x14000
	v_add_u32_e32 v140, s93, v143
	s_add_i32 s71, s71, s54
	ds_read_b128 v[210:213], v140
	ds_read_b128 v[214:217], v140 offset:1024
	ds_read_b128 v[218:221], v140 offset:2048
	ds_read_b128 v[246:249], v140 offset:3072
	v_lshl_add_u64 v[140:141], s[52:53], 0, v[0:1]
	s_mov_b32 m0, s71
	v_lshl_add_u64 v[160:161], s[52:53], 0, v[130:131]
	global_load_lds_dwordx4 v[140:141], off
	s_add_i32 m0, s71, 0x2000
	s_nop 0
	global_load_lds_dwordx4 v[160:161], off
	s_barrier
	s_waitcnt lgkmcnt(0)
	s_waitcnt lgkmcnt(0)
	v_mfma_f32_16x16x32_bf16 v[118:121], v[210:213], v[178:181], v[118:121]
	v_mfma_f32_16x16x32_bf16 v[114:117], v[218:221], v[178:181], v[114:117]
	v_mfma_f32_16x16x32_bf16 v[102:105], v[210:213], v[186:189], v[102:105]
	v_mfma_f32_16x16x32_bf16 v[98:101], v[218:221], v[186:189], v[98:101]
	v_mfma_f32_16x16x32_bf16 v[86:89], v[210:213], v[194:197], v[86:89]
	v_mfma_f32_16x16x32_bf16 v[82:85], v[218:221], v[194:197], v[82:85]
	v_mfma_f32_16x16x32_bf16 v[70:73], v[210:213], v[202:205], v[70:73]
	v_mfma_f32_16x16x32_bf16 v[66:69], v[218:221], v[202:205], v[66:69]
	v_mfma_f32_16x16x32_bf16 v[118:121], v[214:217], v[182:185], v[118:121]
	v_mfma_f32_16x16x32_bf16 v[114:117], v[246:249], v[182:185], v[114:117]
	v_mfma_f32_16x16x32_bf16 v[102:105], v[214:217], v[190:193], v[102:105]
	v_mfma_f32_16x16x32_bf16 v[98:101], v[246:249], v[190:193], v[98:101]
	v_mfma_f32_16x16x32_bf16 v[86:89], v[214:217], v[198:201], v[86:89]
	v_mfma_f32_16x16x32_bf16 v[82:85], v[246:249], v[198:201], v[82:85]
	v_mfma_f32_16x16x32_bf16 v[70:73], v[214:217], v[206:209], v[70:73]
	v_mfma_f32_16x16x32_bf16 v[66:69], v[246:249], v[206:209], v[66:69]
	s_mov_b32 m0, s55
	v_lshl_add_u64 v[222:223], s[46:47], 0, v[0:1]
	s_barrier
	ds_read_b128 v[178:181], v147 offset:16384
	ds_read_b128 v[182:185], v147 offset:17408
	ds_read_b128 v[186:189], v147 offset:18432
	ds_read_b128 v[190:193], v147 offset:19456
	ds_read_b128 v[194:197], v147 offset:20480
	ds_read_b128 v[198:201], v147 offset:21504
	ds_read_b128 v[202:205], v147 offset:22528
	ds_read_b128 v[206:209], v147 offset:23552
	global_load_lds_dwordx4 v[222:223], off
	v_lshl_add_u64 v[242:243], s[46:47], 0, v[130:131]
	s_mov_b32 m0, s58
	s_nop 0
	global_load_lds_dwordx4 v[242:243], off
	s_barrier
	s_waitcnt lgkmcnt(0)
	s_waitcnt lgkmcnt(0)
	v_mfma_f32_16x16x32_bf16 v[62:65], v[148:151], v[178:181], v[62:65]
	v_mfma_f32_16x16x32_bf16 v[58:61], v[156:159], v[178:181], v[58:61]
	v_mfma_f32_16x16x32_bf16 v[46:49], v[148:151], v[186:189], v[46:49]
	v_mfma_f32_16x16x32_bf16 v[42:45], v[156:159], v[186:189], v[42:45]
	v_mfma_f32_16x16x32_bf16 v[30:33], v[148:151], v[194:197], v[30:33]
	v_mfma_f32_16x16x32_bf16 v[26:29], v[156:159], v[194:197], v[26:29]
	v_mfma_f32_16x16x32_bf16 v[14:17], v[148:151], v[202:205], v[14:17]
	v_mfma_f32_16x16x32_bf16 v[10:13], v[156:159], v[202:205], v[10:13]
	v_mfma_f32_16x16x32_bf16 v[62:65], v[152:155], v[182:185], v[62:65]
	v_mfma_f32_16x16x32_bf16 v[58:61], v[172:175], v[182:185], v[58:61]
	v_mfma_f32_16x16x32_bf16 v[46:49], v[152:155], v[190:193], v[46:49]
	v_mfma_f32_16x16x32_bf16 v[42:45], v[172:175], v[190:193], v[42:45]
	v_mfma_f32_16x16x32_bf16 v[30:33], v[152:155], v[198:201], v[30:33]
	v_mfma_f32_16x16x32_bf16 v[26:29], v[172:175], v[198:201], v[26:29]
	v_mfma_f32_16x16x32_bf16 v[14:17], v[152:155], v[206:209], v[14:17]
	v_mfma_f32_16x16x32_bf16 v[10:13], v[172:175], v[206:209], v[10:13]
	s_barrier
; #define PG8_STAGE(bufoff, gbase, voff) do { _Pragma("unroll") for (int _i = 0; _i < 2; ++_i) \
;         __builtin_amdgcn_global_load_lds((const unsigned*)((const char*)(gbase) + (voff)[_i]), (LAS unsigned*)(lds + (bufoff) + ldsw + _i * 8192), 16, 0, 0); } while (0)
; #define PG8_LDA(dst, b, h) do { _Pragma("unroll") for (int m = 0; m < 4; ++m) _Pragma("unroll") for (int k = 0; k < 2; ++k) dst[m][k] = *(const LAS bf16x8*)(lds + PG8_SA(b, h) + aoff + m * 2048 + k * 1024); } while (0)
; #define PG8_LDB(dst, b, h) do { _Pragma("unroll") for (int n = 0; n < 2; ++n) _Pragma("unroll") for (int k = 0; k < 2; ++k) dst[n][k] = *(const LAS bf16x8*)(lds + PG8_SB(b, h) + boff + n * 2048 + k * 1024); } while (0)
; #define PG8_MMA(ai, bj, At, Bt) do { __builtin_amdgcn_s_setprio(1); _Pragma("unroll") for (int m = 0; m < 4; ++m) _Pragma("unroll") for (int n = 0; n < 2; ++n) _Pragma("unroll") for (int k = 0; k < 2; ++k) \
;         acc[ai][bj][m][n] = __builtin_amdgcn_mfma_f32_16x16x32_bf16(Bt[n][k], At[m][k], acc[ai][bj][m][n], 0, 0, 0); __builtin_amdgcn_s_setprio(0); } while (0)
; #define PG8_WAIT_V(n) asm volatile("s_waitcnt vmcnt(" #n ")" ::: "memory")
; #define PG8_WAIT_L(n) asm volatile("s_waitcnt lgkmcnt(" #n ")" ::: "memory")
; #define PG8_BAR __builtin_amdgcn_s_barrier()
; #define PG8_SCHED __builtin_amdgcn_sched_barrier(0)
; template <class Epi>
; __device__ __forceinline__ void gemm_phase(LAS unsigned char* lds, const Gemm g, const StaticOrder& S, const Epi& E) {
;     ...
;             PG8_STAGE(PG8_SB(0, 1), b2 + hstep, voffB);
;             PG8_WAIT_V(6); PG8_BAR; PG8_MMA(1, 1, At, B1); PG8_BAR;
;             PG8_LDB(B0, 1, 0); PG8_SCHED; PG8_LDA(At, 1, 0); PG8_STAGE(PG8_SA(0, 1), a2 + hstep, voffA);
;             PG8_WAIT_L(8); PG8_BAR; PG8_WAIT_L(0); PG8_MMA(0, 0, At, B0); PG8_BAR; PG8_SCHED;
;             PG8_LDB(B1, 1, 1); PG8_STAGE(PG8_SB(1, 0), b3, voffB);
;             PG8_BAR; PG8_WAIT_L(0); PG8_MMA(0, 1, At, B1); PG8_BAR;
;             PG8_LDA(At, 1, 1); PG8_STAGE(PG8_SA(1, 0), a3, voffA);
;             PG8_BAR; PG8_WAIT_L(0); PG8_MMA(1, 0, At, B0); PG8_BAR; PG8_SCHED;
	s_add_u32 s94, s52, 0x60000
	s_addc_u32 s95, s53, 0
	s_add_i32 s71, s93, s54
	v_lshl_add_u64 v[148:149], s[94:95], 0, v[0:1]
	s_mov_b32 m0, s71
	s_nop 0
	global_load_lds_dwordx4 v[148:149], off
	v_lshl_add_u64 v[148:149], s[94:95], 0, v[130:131]
	s_add_i32 m0, s71, 0x2000
	s_nop 0
	global_load_lds_dwordx4 v[148:149], off
	s_waitcnt vmcnt(6)
	s_barrier
	v_mfma_f32_16x16x32_bf16 v[54:57], v[210:213], v[178:181], v[54:57]
	v_mfma_f32_16x16x32_bf16 v[50:53], v[218:221], v[178:181], v[50:53]
	v_mfma_f32_16x16x32_bf16 v[38:41], v[210:213], v[186:189], v[38:41]
	v_mfma_f32_16x16x32_bf16 v[34:37], v[218:221], v[186:189], v[34:37]
	v_mfma_f32_16x16x32_bf16 v[22:25], v[210:213], v[194:197], v[22:25]
	v_mfma_f32_16x16x32_bf16 v[18:21], v[218:221], v[194:197], v[18:21]
	v_mfma_f32_16x16x32_bf16 v[6:9], v[210:213], v[202:205], v[6:9]
	v_mfma_f32_16x16x32_bf16 v[2:5], v[218:221], v[202:205], v[2:5]
	v_mfma_f32_16x16x32_bf16 v[54:57], v[214:217], v[182:185], v[54:57]
	v_mfma_f32_16x16x32_bf16 v[50:53], v[246:249], v[182:185], v[50:53]
	v_mfma_f32_16x16x32_bf16 v[38:41], v[214:217], v[190:193], v[38:41]
	v_mfma_f32_16x16x32_bf16 v[34:37], v[246:249], v[190:193], v[34:37]
	v_mfma_f32_16x16x32_bf16 v[22:25], v[214:217], v[198:201], v[22:25]
	v_mfma_f32_16x16x32_bf16 v[18:21], v[246:249], v[198:201], v[18:21]
	v_mfma_f32_16x16x32_bf16 v[6:9], v[214:217], v[206:209], v[6:9]
	v_mfma_f32_16x16x32_bf16 v[2:5], v[246:249], v[206:209], v[2:5]
	s_add_i32 s71, 0, 0x18000
	v_add_u32_e32 v172, s71, v143
	s_barrier
	ds_read_b128 v[148:151], v172
	ds_read_b128 v[152:155], v172 offset:1024
	ds_read_b128 v[156:159], v172 offset:2048
	ds_read_b128 v[172:175], v172 offset:3072
	s_add_u32 s46, s46, 0x60000
	s_addc_u32 s47, s47, 0
	s_mov_b32 m0, s59
	v_lshl_add_u64 v[210:211], s[46:47], 0, v[0:1]
	ds_read_b128 v[178:181], v147 offset:32768
	ds_read_b128 v[182:185], v147 offset:33792
	ds_read_b128 v[186:189], v147 offset:34816
	ds_read_b128 v[190:193], v147 offset:35840
	ds_read_b128 v[194:197], v147 offset:36864
	ds_read_b128 v[198:201], v147 offset:37888
	ds_read_b128 v[202:205], v147 offset:38912
	ds_read_b128 v[206:209], v147 offset:39936
	global_load_lds_dwordx4 v[210:211], off
	v_lshl_add_u64 v[210:211], s[46:47], 0, v[130:131]
	s_mov_b32 m0, s61
	s_nop 0
	global_load_lds_dwordx4 v[210:211], off
	s_waitcnt lgkmcnt(8)
	s_barrier
	s_waitcnt lgkmcnt(0)
	s_waitcnt lgkmcnt(0)
	v_mfma_f32_16x16x32_bf16 v[126:129], v[148:151], v[178:181], v[126:129]
	v_mfma_f32_16x16x32_bf16 v[122:125], v[156:159], v[178:181], v[122:125]
	v_mfma_f32_16x16x32_bf16 v[110:113], v[148:151], v[186:189], v[110:113]
	v_mfma_f32_16x16x32_bf16 v[106:109], v[156:159], v[186:189], v[106:109]
	v_mfma_f32_16x16x32_bf16 v[94:97], v[148:151], v[194:197], v[94:97]
	v_mfma_f32_16x16x32_bf16 v[90:93], v[156:159], v[194:197], v[90:93]
	v_mfma_f32_16x16x32_bf16 v[78:81], v[148:151], v[202:205], v[78:81]
	v_mfma_f32_16x16x32_bf16 v[74:77], v[156:159], v[202:205], v[74:77]
	v_mfma_f32_16x16x32_bf16 v[126:129], v[152:155], v[182:185], v[126:129]
	v_mfma_f32_16x16x32_bf16 v[122:125], v[172:175], v[182:185], v[122:125]
	v_mfma_f32_16x16x32_bf16 v[110:113], v[152:155], v[190:193], v[110:113]
	v_mfma_f32_16x16x32_bf16 v[106:109], v[172:175], v[190:193], v[106:109]
	v_mfma_f32_16x16x32_bf16 v[94:97], v[152:155], v[198:201], v[94:97]
	v_mfma_f32_16x16x32_bf16 v[90:93], v[172:175], v[198:201], v[90:93]
	v_mfma_f32_16x16x32_bf16 v[78:81], v[152:155], v[206:209], v[78:81]
	v_mfma_f32_16x16x32_bf16 v[74:77], v[172:175], v[206:209], v[74:77]
	s_barrier
	s_add_i32 s93, 0, 0x1c000
	s_add_i32 s46, s71, s54
	v_add_u32_e32 v177, s93, v143
	v_lshl_add_u64 v[140:141], v[140:141], 0, s[28:29]
	s_mov_b32 m0, s46
	ds_read_b128 v[210:213], v177
	ds_read_b128 v[214:217], v177 offset:1024
	ds_read_b128 v[218:221], v177 offset:2048
	ds_read_b128 v[246:249], v177 offset:3072
	global_load_lds_dwordx4 v[140:141], off
	v_lshl_add_u64 v[140:141], v[160:161], 0, s[28:29]
	s_add_i32 m0, s46, 0x2000
	s_nop 0
	global_load_lds_dwordx4 v[140:141], off
	s_barrier
	s_waitcnt lgkmcnt(0)
	s_waitcnt lgkmcnt(0)
	v_mfma_f32_16x16x32_bf16 v[118:121], v[210:213], v[178:181], v[118:121]
	v_mfma_f32_16x16x32_bf16 v[114:117], v[218:221], v[178:181], v[114:117]
	v_mfma_f32_16x16x32_bf16 v[102:105], v[210:213], v[186:189], v[102:105]
	v_mfma_f32_16x16x32_bf16 v[98:101], v[218:221], v[186:189], v[98:101]
	v_mfma_f32_16x16x32_bf16 v[86:89], v[210:213], v[194:197], v[86:89]
	v_mfma_f32_16x16x32_bf16 v[82:85], v[218:221], v[194:197], v[82:85]
	v_mfma_f32_16x16x32_bf16 v[70:73], v[210:213], v[202:205], v[70:73]
	v_mfma_f32_16x16x32_bf16 v[66:69], v[218:221], v[202:205], v[66:69]
	v_mfma_f32_16x16x32_bf16 v[118:121], v[214:217], v[182:185], v[118:121]
	v_mfma_f32_16x16x32_bf16 v[114:117], v[246:249], v[182:185], v[114:117]
	v_mfma_f32_16x16x32_bf16 v[102:105], v[214:217], v[190:193], v[102:105]
	v_mfma_f32_16x16x32_bf16 v[98:101], v[246:249], v[190:193], v[98:101]
	v_mfma_f32_16x16x32_bf16 v[86:89], v[214:217], v[198:201], v[86:89]
	v_mfma_f32_16x16x32_bf16 v[82:85], v[246:249], v[198:201], v[82:85]
	v_mfma_f32_16x16x32_bf16 v[70:73], v[214:217], v[206:209], v[70:73]
	v_mfma_f32_16x16x32_bf16 v[66:69], v[246:249], v[206:209], v[66:69]
	s_mov_b32 m0, s62
	v_lshl_add_u64 v[140:141], v[222:223], 0, s[28:29]
	s_barrier
	ds_read_b128 v[178:181], v147 offset:49152
	ds_read_b128 v[182:185], v147 offset:50176
	ds_read_b128 v[186:189], v147 offset:51200
	ds_read_b128 v[190:193], v147 offset:52224
	ds_read_b128 v[194:197], v147 offset:53248
	ds_read_b128 v[198:201], v147 offset:54272
	ds_read_b128 v[202:205], v147 offset:55296
	ds_read_b128 v[206:209], v147 offset:56320
	global_load_lds_dwordx4 v[140:141], off
	v_lshl_add_u64 v[140:141], v[242:243], 0, s[28:29]
	s_mov_b32 m0, s63
	s_nop 0
	global_load_lds_dwordx4 v[140:141], off
	s_barrier
; __device__ __forceinline__ u64 ss_fix(float ss) { return (u64)(ss * 1048576.f + 0.5f); }
; __device__ __forceinline__ unsigned pk2(float lo, float hi) { unsigned r; asm volatile("v_cvt_pk_bf16_f32 %0, %1, %2" : "=v"(r) : "v"(lo), "v"(hi)); return r; }
; __device__ __forceinline__ float shfl_xor_(float v, int o, int lane) { return shfl_idx(v, lane ^ o); }
; #define PG8_STAGE(bufoff, gbase, voff) do { _Pragma("unroll") for (int _i = 0; _i < 2; ++_i) \
;         __builtin_amdgcn_global_load_lds((const unsigned*)((const char*)(gbase) + (voff)[_i]), (LAS unsigned*)(lds + (bufoff) + ldsw + _i * 8192), 16, 0, 0); } while (0)
; template <class Epi>
; __device__ __forceinline__ void gemm_phase(LAS unsigned char* lds, const Gemm g, const StaticOrder& S, const Epi& E) {
;     ...
;             PG8_BAR; PG8_WAIT_L(0); PG8_MMA(0, 1, At, B1); PG8_BAR;
;             PG8_LDA(At, 1, 1); PG8_STAGE(PG8_SA(1, 0), a3, voffA);
;             PG8_BAR; PG8_WAIT_L(0); PG8_MMA(1, 0, At, B0); PG8_BAR; PG8_SCHED;
;             PG8_STAGE(PG8_SB(1, 1), b3 + hstep, voffB);
;             PG8_WAIT_V(6); PG8_BAR; PG8_MMA(1, 1, At, B1); PG8_BAR;
;         }
;         if constexpr (Epi::AFTER_DRAIN) { if (has_next) E(acc, cur, wr, wc, fr, fq); } else E(acc, cur, wr, wc, fr, fq);
;     __device__ __forceinline__ void operator()(const f32x4 (&acc)[2][2][4][2], const Unit& u, int wr, int wc, int fr, int fq) const {
;         const int row0 = u.pm * BM + wr * 64 + fr, col0 = u.pn * BM + wc * 32 + 4 * fq, lane = fr | (fq << 4);
; #pragma unroll
;         for (int ai = 0; ai < 2; ++ai)
; #pragma unroll
;             for (int m = 0; m < 4; ++m) { const int row = row0 + ai * HALF + m * 16; bf16_t* xbp = xb + (size_t)row * ldc + col0;
;                 float ss = 0.f;
; #pragma unroll
;                 for (int bj = 0; bj < 2; ++bj)
; #pragma unroll
;                     for (int n = 0; n < 2; ++n) { u32x2* pp = (u32x2*)(xbp + bj * HALF + n * 16); float o[4]; unpack4(*pp, o);
;                         u32x2 w; w.x = pk2(o[0] + acc[ai][bj][m][n][0], o[1] + acc[ai][bj][m][n][1]); w.y = pk2(o[2] + acc[ai][bj][m][n][2], o[3] + acc[ai][bj][m][n][3]); *pp = w;
;                         unpack4(w, o); ss += o[0] * o[0] + o[1] * o[1] + o[2] * o[2] + o[3] * o[3]; }
;                 ss += shfl_xor_(ss, 16, lane); ss += shfl_xor_(ss, 32, lane);
;                 if (fq == 0) atomicAdd(rss + row, ss_fix(ss)); }
	s_waitcnt lgkmcnt(0)
	s_waitcnt lgkmcnt(0)
	v_mfma_f32_16x16x32_bf16 v[62:65], v[148:151], v[178:181], v[62:65]
	v_mfma_f32_16x16x32_bf16 v[58:61], v[156:159], v[178:181], v[58:61]
	v_mfma_f32_16x16x32_bf16 v[46:49], v[148:151], v[186:189], v[46:49]
	v_mfma_f32_16x16x32_bf16 v[42:45], v[156:159], v[186:189], v[42:45]
	v_mfma_f32_16x16x32_bf16 v[30:33], v[148:151], v[194:197], v[30:33]
	v_mfma_f32_16x16x32_bf16 v[26:29], v[156:159], v[194:197], v[26:29]
	v_mfma_f32_16x16x32_bf16 v[14:17], v[148:151], v[202:205], v[14:17]
	v_mfma_f32_16x16x32_bf16 v[10:13], v[156:159], v[202:205], v[10:13]
	v_mfma_f32_16x16x32_bf16 v[62:65], v[152:155], v[182:185], v[62:65]
	v_mfma_f32_16x16x32_bf16 v[58:61], v[172:175], v[182:185], v[58:61]
	v_mfma_f32_16x16x32_bf16 v[46:49], v[152:155], v[190:193], v[46:49]
	v_mfma_f32_16x16x32_bf16 v[42:45], v[172:175], v[190:193], v[42:45]
	v_mfma_f32_16x16x32_bf16 v[30:33], v[152:155], v[198:201], v[30:33]
	v_mfma_f32_16x16x32_bf16 v[26:29], v[172:175], v[198:201], v[26:29]
	v_mfma_f32_16x16x32_bf16 v[14:17], v[152:155], v[206:209], v[14:17]
	v_mfma_f32_16x16x32_bf16 v[10:13], v[172:175], v[206:209], v[10:13]
	s_barrier
	s_add_u32 s46, s52, 0x60080
	s_addc_u32 s47, s53, 0
	s_add_i32 s52, s93, s54
	v_lshl_add_u64 v[140:141], s[46:47], 0, v[0:1]
	s_mov_b32 m0, s52
	s_nop 0
	global_load_lds_dwordx4 v[140:141], off
	v_lshl_add_u64 v[140:141], s[46:47], 0, v[130:131]
	s_add_i32 m0, s52, 0x2000
	s_nop 0
	global_load_lds_dwordx4 v[140:141], off
	s_waitcnt vmcnt(6)
	s_barrier
	v_mfma_f32_16x16x32_bf16 v[54:57], v[210:213], v[178:181], v[54:57]
	v_mfma_f32_16x16x32_bf16 v[50:53], v[218:221], v[178:181], v[50:53]
	v_mfma_f32_16x16x32_bf16 v[38:41], v[210:213], v[186:189], v[38:41]
	v_mfma_f32_16x16x32_bf16 v[34:37], v[218:221], v[186:189], v[34:37]
	v_mfma_f32_16x16x32_bf16 v[22:25], v[210:213], v[194:197], v[22:25]
	v_mfma_f32_16x16x32_bf16 v[18:21], v[218:221], v[194:197], v[18:21]
	v_mfma_f32_16x16x32_bf16 v[6:9], v[210:213], v[202:205], v[6:9]
	v_mfma_f32_16x16x32_bf16 v[2:5], v[218:221], v[202:205], v[2:5]
	v_mfma_f32_16x16x32_bf16 v[54:57], v[214:217], v[182:185], v[54:57]
	v_mfma_f32_16x16x32_bf16 v[50:53], v[246:249], v[182:185], v[50:53]
	v_mfma_f32_16x16x32_bf16 v[38:41], v[214:217], v[190:193], v[38:41]
	v_mfma_f32_16x16x32_bf16 v[34:37], v[246:249], v[190:193], v[34:37]
	v_mfma_f32_16x16x32_bf16 v[22:25], v[214:217], v[198:201], v[22:25]
	v_mfma_f32_16x16x32_bf16 v[18:21], v[246:249], v[198:201], v[18:21]
	v_mfma_f32_16x16x32_bf16 v[6:9], v[214:217], v[206:209], v[6:9]
	v_mfma_f32_16x16x32_bf16 v[2:5], v[246:249], v[206:209], v[2:5]
	s_add_i32 s70, s70, 2
	s_add_u32 s50, s50, 0x100
	s_addc_u32 s51, s51, 0
	s_cmp_gt_u32 s70, 21
	s_barrier
	s_cbranch_scc0 .LBB0_258
	s_add_u32 s46, s68, 0xffffff00
	s_addc_u32 s47, s69, -1
	s_and_b64 vcc, exec, s[0:1]
	s_cbranch_vccz .LBB0_277
	v_lshl_add_u32 v140, s66, 8, v142
	v_ashrrev_i32_e32 v141, 31, v140
	v_readlane_b32 s0, v252, 51
	v_lshl_or_b32 v138, s65, 8, v144
	v_lshlrev_b64 v[136:137], 11, v[140:141]
	v_readlane_b32 s1, v252, 52
	v_ashrrev_i32_e32 v139, 31, v138
	s_nop 0
	v_lshl_add_u64 v[136:137], s[0:1], 0, v[136:137]
	v_lshl_add_u64 v[136:137], v[138:139], 1, v[136:137]
	global_load_dwordx2 v[148:149], v[136:137], off
	s_waitcnt vmcnt(0)
	v_lshlrev_b32_e32 v150, 16, v148
	v_and_b32_e32 v148, 0xffff0000, v148
	v_lshlrev_b32_e32 v151, 16, v149
	v_and_b32_e32 v149, 0xffff0000, v149
	v_add_f32_e32 v126, v126, v150
	v_add_f32_e32 v127, v127, v148
	v_add_f32_e32 v128, v128, v151
	v_add_f32_e32 v129, v129, v149
	v_cvt_pk_bf16_f32 v126, v126, v127
	v_cvt_pk_bf16_f32 v127, v128, v129
	global_load_dwordx2 v[128:129], v[136:137], off offset:32
	s_waitcnt vmcnt(0)
	v_lshlrev_b32_e32 v148, 16, v128
	v_and_b32_e32 v128, 0xffff0000, v128
	v_lshlrev_b32_e32 v149, 16, v129
	v_and_b32_e32 v129, 0xffff0000, v129
	v_add_f32_e32 v122, v122, v148
	v_add_f32_e32 v123, v123, v128
	v_add_f32_e32 v124, v124, v149
	v_add_f32_e32 v125, v125, v129
	global_store_dwordx2 v[136:137], v[126:127], off
	v_cvt_pk_bf16_f32 v122, v122, v123
	v_cvt_pk_bf16_f32 v123, v124, v125
	global_load_dwordx2 v[124:125], v[136:137], off offset:256
	s_waitcnt vmcnt(0)
	v_lshlrev_b32_e32 v128, 16, v124
	v_and_b32_e32 v124, 0xffff0000, v124
	v_lshlrev_b32_e32 v129, 16, v125
	v_and_b32_e32 v125, 0xffff0000, v125
	v_add_f32_e32 v118, v118, v128
	v_add_f32_e32 v119, v119, v124
	v_add_f32_e32 v120, v120, v129
	v_add_f32_e32 v121, v121, v125
	global_store_dwordx2 v[136:137], v[122:123], off offset:32
	v_cvt_pk_bf16_f32 v118, v118, v119
	v_cvt_pk_bf16_f32 v119, v120, v121
	global_load_dwordx2 v[120:121], v[136:137], off offset:288
	v_and_b32_e32 v125, 0xffff0000, v126
	v_lshlrev_b32_e32 v124, 16, v126
	v_mul_f32_e32 v125, v125, v125
	v_fmac_f32_e32 v125, v124, v124
	v_lshlrev_b32_e32 v124, 16, v122
	v_and_b32_e32 v122, 0xffff0000, v122
	v_lshlrev_b32_e32 v126, 16, v127
	v_mul_f32_e32 v122, v122, v122
	v_fmac_f32_e32 v125, v126, v126
	v_lshlrev_b32_e32 v126, 16, v123
	v_fmac_f32_e32 v122, v124, v124
	v_and_b32_e32 v123, 0xffff0000, v123
	v_fmac_f32_e32 v122, v126, v126
	v_fmac_f32_e32 v122, v123, v123
	global_store_dwordx2 v[136:137], v[118:119], off offset:256
	v_lshlrev_b32_e32 v123, 16, v118
	v_and_b32_e32 v118, 0xffff0000, v118
	v_mul_f32_e32 v118, v118, v118
	v_and_b32_e32 v127, 0xffff0000, v127
	v_lshlrev_b32_e32 v124, 16, v119
	v_fmac_f32_e32 v118, v123, v123
	v_fmac_f32_e32 v125, v127, v127
	v_and_b32_e32 v119, 0xffff0000, v119
	v_fmac_f32_e32 v118, v124, v124
	v_add_f32_e32 v122, v125, v122
	v_fmac_f32_e32 v118, v119, v119
	v_add_f32_e32 v118, v122, v118
	s_waitcnt vmcnt(0)
	v_lshlrev_b32_e32 v119, 16, v120
	v_and_b32_e32 v120, 0xffff0000, v120
	v_lshlrev_b32_e32 v122, 16, v121
	v_and_b32_e32 v121, 0xffff0000, v121
	v_add_f32_e32 v114, v114, v119
	v_add_f32_e32 v115, v115, v120
	v_add_f32_e32 v117, v117, v121
	v_add_f32_e32 v116, v116, v122
	v_cvt_pk_bf16_f32 v114, v114, v115
	v_cvt_pk_bf16_f32 v115, v116, v117
	global_store_dwordx2 v[136:137], v[114:115], off offset:288
	v_and_b32_e32 v117, 0xffff0000, v114
	v_lshlrev_b32_e32 v116, 16, v114
	v_mul_f32_e32 v117, v117, v117
	v_lshlrev_b32_e32 v119, 16, v115
	v_fmac_f32_e32 v117, v116, v116
	v_and_b32_e32 v120, 0xffff0000, v115
	v_fmac_f32_e32 v117, v119, v119
	v_fmac_f32_e32 v117, v120, v120
	v_add_f32_e32 v116, v118, v117
	ds_bpermute_b32 v117, v145, v116
	v_lshl_add_u64 v[114:115], v[140:141], 3, s[76:77]
	s_waitcnt lgkmcnt(0)
	v_add_f32_e32 v116, v116, v117
	ds_bpermute_b32 v117, v146, v116
	s_and_saveexec_b64 s[0:1], s[40:41]
	v_readlane_b32 s94, v254, 32
	s_movk_i32 s93, 0x1000
	v_readlane_b32 s95, v254, 33
	s_cbranch_execz .LBB0_262
	s_waitcnt lgkmcnt(0)
	v_add_f32_e32 v116, v116, v117
	s_mov_b32 s46, 0x49800000
	v_fma_f32 v116, v116, s46, 0.5
	v_trunc_f32_e32 v116, v116
	v_mul_f32_e32 v117, 0x2f800000, v116
	v_floor_f32_e32 v117, v117
	v_fmac_f32_e32 v116, 0xcf800000, v117
	v_cvt_u32_f32_e32 v116, v116
	v_cvt_u32_f32_e32 v117, v117
	global_atomic_add_x2 v[114:115], v[116:117], off

; #define LAS __attribute__((address_space(3)))
; #define TIDX opaque_tid()
; template <int K, int MODE  >
; __device__ __forceinline__ void thin_gemm(LAS unsigned char* lds, const bf16_t* A, const bf16_t* Bt, int N, void* out, int ldc, bf16_t* xb, u64* rss) {
;     const int tid = TIDX, wid = tid >> 6, lane = tid & 63, fr = lane & 15, fq = lane >> 4;
;     constexpr int KW = K / 8, STEPS = KW / 32;
;     const int ntask = (N / 16) * 8;
;     LAS f32x4* red = (LAS f32x4*)lds;
;     const int per = (ntask + (int)gridDim.x - 1) / (int)gridDim.x, t0 = blockIdx.x * per, t1 = min(ntask, t0 + per);
;     for (int base = t0; base < t1; base += 8) {
;         const int nr = min(8, t1 - base);
; #pragma unroll (STEPS <= 4 ? 4 : 2)
;         for (int i = 0; i < nr; ++i) {
;             const int t = base + i, ct = t >> 3, rt = t & 7;
;             const bf16_t* ap = A + (size_t)(rt * 16 + fr) * K + wid * KW + 8 * fq;
;             const bf16_t* bp = Bt + (size_t)(ct * 16 + fr) * K + wid * KW + 8 * fq;
.LBB0_286:
	s_setprio 0
	v_readlane_b32 s0, v253, 6
	v_readlane_b32 s1, v253, 7
	v_mov_b32_e32 v10, v163
	s_andn2_b64 vcc, exec, s[0:1]
	v_readlane_b32 s42, v253, 8
	s_cbranch_vccnz .LBB0_295
	v_ashrrev_i32_e32 v6, 6, v10
	s_movk_i32 s0, 0xc0
	s_waitcnt lgkmcnt(0)
	v_mul_lo_u32 v2, v6, s0
	v_ashrrev_i32_e32 v3, 31, v2
	v_readlane_b32 s0, v250, 45
	v_lshlrev_b64 v[4:5], 1, v[2:3]
	v_readlane_b32 s1, v250, 46
	v_and_b32_e32 v13, 63, v10
	v_and_b32_e32 v0, 48, v10
	v_lshl_add_u64 v[2:3], s[0:1], 0, v[4:5]
	v_lshl_add_u64 v[4:5], s[56:57], 0, v[4:5]
	v_lshl_add_u32 v9, v13, 4, 0
	v_lshl_add_u64 v[2:3], v[2:3], 0, v[0:1]
	v_lshl_add_u64 v[4:5], v[4:5], 0, v[0:1]
	v_and_b32_e32 v0, 0xfffffc0, v10
	v_lshl_add_u32 v8, v0, 4, v9
	v_lshrrev_b32_e32 v0, 2, v10
	v_and_b32_e32 v7, 15, v10
	v_and_b32_e32 v10, 12, v0
	v_lshlrev_b32_e32 v0, 2, v13
	v_lshl_add_u32 v9, v6, 13, v9
	v_xor_b32_e32 v11, 64, v0
	v_xor_b32_e32 v12, 0x80, v0
	v_cmp_gt_u32_e32 vcc, 16, v13
	v_readlane_b32 s2, v253, 35
	v_readlane_b32 s3, v253, 33
	v_readlane_b32 s24, v253, 9
	v_readlane_b32 s26, v253, 34
	s_branch .LBB0_289
